# baseline (speedup 1.0000x reference)
; #define PG8_STAGE(bufoff, gbase, voff) do { _Pragma("unroll") for (int _i = 0; _i < 2; ++_i) \
;         __builtin_amdgcn_global_load_lds((const unsigned*)((const char*)(gbase) + (voff)[_i]), (PG8_LAS unsigned*)(lds + (bufoff) + ldsw + _i * 8192), 16, 0, 0); } while (0)
; #define PG8_LDA(dst, b, h) do { _Pragma("unroll") for (int m = 0; m < 4; ++m) _Pragma("unroll") for (int k = 0; k < 2; ++k) dst[m][k] = *(const PG8_LAS bf16x8*)(lds + PG8_SA(b, h) + aoff + m * 2048 + k * 1024); } while (0)
; #define PG8_LDB(dst, b, h) do { _Pragma("unroll") for (int n = 0; n < 2; ++n) _Pragma("unroll") for (int k = 0; k < 2; ++k) dst[n][k] = *(const PG8_LAS bf16x8*)(lds + PG8_SB(b, h) + boff + n * 2048 + k * 1024); } while (0)
; #define PG8_MMA(ai, bj, At, Bt) do { __builtin_amdgcn_s_setprio(1); _Pragma("unroll") for (int m = 0; m < 4; ++m) _Pragma("unroll") for (int n = 0; n < 2; ++n) _Pragma("unroll") for (int k = 0; k < 2; ++k) \
;         acc[ai][bj][m][n] = __builtin_amdgcn_mfma_f32_16x16x32_bf16(Bt[n][k], At[m][k], acc[ai][bj][m][n], 0, 0, 0); __builtin_amdgcn_s_setprio(0); } while (0)
; #define PG8_WAIT_V(n) asm volatile("s_waitcnt vmcnt(" #n ")" ::: "memory")
; #define PG8_WAIT_L(n) asm volatile("s_waitcnt lgkmcnt(" #n ")" ::: "memory")
; #define PG8_BAR __builtin_amdgcn_s_barrier()
; #define PG8_SCHED __builtin_amdgcn_sched_barrier(0)
; template <class Epi, class Sched, bool ALIGN_EPI = false, bool SP2 = false>
; __device__ __forceinline__ void gemm_phase(PG8_LAS unsigned char* lds, const Gemm g, const Sched& S, const Epi& E) {
;     ...
;             PG8_LDB(B0, 0, 0); PG8_LDB(B1, 0, 1); PG8_SCHED; PG8_LDA(At, 0, 0); PG8_STAGE(PG8_SA(1, 1), a1 + hstep, voffA);
;             PG8_WAIT_V(8); PG8_WAIT_L(0); PG8_BAR; PG8_MMA(0, 0, At, B0); PG8_MMA(0, 1, At, B1); PG8_BAR; PG8_SCHED;
;             PG8_LDA(At, 0, 1); PG8_STAGE(PG8_SB(0, 0), b2, voffB); PG8_STAGE(PG8_SB(0, 1), b2 + hstep, voffB); PG8_STAGE(PG8_SA(0, 0), a2, voffA);
;             PG8_WAIT_V(8); PG8_WAIT_L(0); PG8_BAR; PG8_MMA(1, 0, At, B0); PG8_MMA(1, 1, At, B1); PG8_BAR; PG8_SCHED;
.LBB0_65:
	s_add_u32 s8, s6, 0xfff80080
	s_addc_u32 s9, s7, -1
	s_add_i32 s79, 0, 0x10000
	s_cmp_eq_u32 s78, 28
	s_cselect_b32 s41, s73, s9
	s_cselect_b32 s40, s74, s8
	s_cselect_b32 s9, s25, s77
	s_cselect_b32 s8, s75, s76
	s_add_i32 s82, 0, 0x14000
	v_add_u32_e32 v140, s79, v212
	v_add_u32_e32 v156, s82, v212
	ds_read_b128 v[128:131], v140
	ds_read_b128 v[132:135], v140 offset:1024
	ds_read_b128 v[136:139], v140 offset:2048
	ds_read_b128 v[140:143], v140 offset:3072
	ds_read_b128 v[144:147], v156
	ds_read_b128 v[148:151], v156 offset:1024
	ds_read_b128 v[152:155], v156 offset:2048
	ds_read_b128 v[156:159], v156 offset:3072
	v_lshl_add_u64 v[198:199], s[6:7], 0, v[174:175]
	s_add_i32 m0, s59, 0xc000
	ds_read_b128 v[160:163], v213
	ds_read_b128 v[164:167], v213 offset:1024
	ds_read_b128 v[178:181], v213 offset:2048
	ds_read_b128 v[182:185], v213 offset:3072
	ds_read_b128 v[186:189], v213 offset:4096
	ds_read_b128 v[190:193], v213 offset:5120
	ds_read_b128 v[194:197], v213 offset:6144
	ds_read_b128 v[214:217], v213 offset:7168
	global_load_lds_dwordx4 v[198:199], off
	v_lshl_add_u64 v[198:199], s[6:7], 0, v[176:177]
	s_add_i32 m0, s59, 0xe000
	s_nop 0
	global_load_lds_dwordx4 v[198:199], off
	s_waitcnt vmcnt(8)
	s_waitcnt lgkmcnt(0)
	s_barrier
	s_setprio 1
	s_waitcnt lgkmcnt(0)
	v_mfma_f32_16x16x32_bf16 v[124:127], v[128:131], v[160:163], v[124:127]
	v_mfma_f32_16x16x32_bf16 v[120:123], v[136:139], v[160:163], v[120:123]
	v_mfma_f32_16x16x32_bf16 v[108:111], v[128:131], v[178:181], v[108:111]
	v_mfma_f32_16x16x32_bf16 v[104:107], v[136:139], v[178:181], v[104:107]
	v_mfma_f32_16x16x32_bf16 v[92:95], v[128:131], v[186:189], v[92:95]
	v_mfma_f32_16x16x32_bf16 v[88:91], v[136:139], v[186:189], v[88:91]
	v_mfma_f32_16x16x32_bf16 v[76:79], v[128:131], v[194:197], v[76:79]
	v_mfma_f32_16x16x32_bf16 v[72:75], v[136:139], v[194:197], v[72:75]
	v_mfma_f32_16x16x32_bf16 v[124:127], v[132:135], v[164:167], v[124:127]
	v_mfma_f32_16x16x32_bf16 v[120:123], v[140:143], v[164:167], v[120:123]
	v_mfma_f32_16x16x32_bf16 v[108:111], v[132:135], v[182:185], v[108:111]
	v_mfma_f32_16x16x32_bf16 v[104:107], v[140:143], v[182:185], v[104:107]
	v_mfma_f32_16x16x32_bf16 v[92:95], v[132:135], v[190:193], v[92:95]
	v_mfma_f32_16x16x32_bf16 v[88:91], v[140:143], v[190:193], v[88:91]
	v_mfma_f32_16x16x32_bf16 v[76:79], v[132:135], v[214:217], v[76:79]
	v_mfma_f32_16x16x32_bf16 v[72:75], v[140:143], v[214:217], v[72:75]
	s_setprio 0
	s_setprio 1
	v_mfma_f32_16x16x32_bf16 v[116:119], v[144:147], v[160:163], v[116:119]
	v_mfma_f32_16x16x32_bf16 v[112:115], v[152:155], v[160:163], v[112:115]
	v_mfma_f32_16x16x32_bf16 v[100:103], v[144:147], v[178:181], v[100:103]
	v_mfma_f32_16x16x32_bf16 v[96:99], v[152:155], v[178:181], v[96:99]
	v_mfma_f32_16x16x32_bf16 v[84:87], v[144:147], v[186:189], v[84:87]
	v_mfma_f32_16x16x32_bf16 v[80:83], v[152:155], v[186:189], v[80:83]
	v_mfma_f32_16x16x32_bf16 v[68:71], v[144:147], v[194:197], v[68:71]
	v_mfma_f32_16x16x32_bf16 v[64:67], v[152:155], v[194:197], v[64:67]
	v_mfma_f32_16x16x32_bf16 v[116:119], v[148:151], v[164:167], v[116:119]
	v_mfma_f32_16x16x32_bf16 v[112:115], v[156:159], v[164:167], v[112:115]
	v_mfma_f32_16x16x32_bf16 v[100:103], v[148:151], v[182:185], v[100:103]
	v_mfma_f32_16x16x32_bf16 v[96:99], v[156:159], v[182:185], v[96:99]
	v_mfma_f32_16x16x32_bf16 v[84:87], v[148:151], v[190:193], v[84:87]
	v_mfma_f32_16x16x32_bf16 v[80:83], v[156:159], v[190:193], v[80:83]
	v_mfma_f32_16x16x32_bf16 v[68:71], v[148:151], v[214:217], v[68:71]
	v_mfma_f32_16x16x32_bf16 v[64:67], v[156:159], v[214:217], v[64:67]
	s_setprio 0
	s_barrier
	s_add_i32 s79, s79, s44
	v_lshl_add_u64 v[198:199], s[8:9], 0, v[200:201]
	s_mov_b32 m0, s79
	ds_read_b128 v[160:163], v213 offset:16384
	ds_read_b128 v[164:167], v213 offset:17408
	ds_read_b128 v[178:181], v213 offset:18432
	ds_read_b128 v[182:185], v213 offset:19456
	ds_read_b128 v[186:189], v213 offset:20480
	ds_read_b128 v[190:193], v213 offset:21504
	ds_read_b128 v[194:197], v213 offset:22528
	ds_read_b128 v[214:217], v213 offset:23552
	global_load_lds_dwordx4 v[198:199], off
	s_add_i32 m0, s79, 0x2000
	s_add_u32 s80, s8, 0x80000
	v_lshl_add_u64 v[218:219], s[8:9], 0, v[168:169]
	s_addc_u32 s81, s9, 0
	s_add_i32 s79, s82, s44
	global_load_lds_dwordx4 v[218:219], off
	v_lshl_add_u64 v[220:221], s[80:81], 0, v[200:201]
	s_mov_b32 m0, s79
	v_lshl_add_u64 v[222:223], s[40:41], 0, v[170:171]
	global_load_lds_dwordx4 v[220:221], off
	v_lshl_add_u64 v[220:221], s[80:81], 0, v[168:169]
	s_add_i32 m0, s79, 0x2000
	s_nop 0
	global_load_lds_dwordx4 v[220:221], off
	v_lshl_add_u64 v[220:221], s[40:41], 0, v[172:173]
	s_mov_b32 m0, s59
	s_nop 0
	global_load_lds_dwordx4 v[220:221], off
	s_mov_b32 m0, s60
	s_nop 0
	global_load_lds_dwordx4 v[222:223], off
	s_waitcnt vmcnt(8)
	s_waitcnt lgkmcnt(0)
	s_barrier
; #define PG8_STAGE(bufoff, gbase, voff) do { _Pragma("unroll") for (int _i = 0; _i < 2; ++_i) \
;         __builtin_amdgcn_global_load_lds((const unsigned*)((const char*)(gbase) + (voff)[_i]), (PG8_LAS unsigned*)(lds + (bufoff) + ldsw + _i * 8192), 16, 0, 0); } while (0)
; #define PG8_LDA(dst, b, h) do { _Pragma("unroll") for (int m = 0; m < 4; ++m) _Pragma("unroll") for (int k = 0; k < 2; ++k) dst[m][k] = *(const PG8_LAS bf16x8*)(lds + PG8_SA(b, h) + aoff + m * 2048 + k * 1024); } while (0)
; #define PG8_LDB(dst, b, h) do { _Pragma("unroll") for (int n = 0; n < 2; ++n) _Pragma("unroll") for (int k = 0; k < 2; ++k) dst[n][k] = *(const PG8_LAS bf16x8*)(lds + PG8_SB(b, h) + boff + n * 2048 + k * 1024); } while (0)
; #define PG8_MMA(ai, bj, At, Bt) do { __builtin_amdgcn_s_setprio(1); _Pragma("unroll") for (int m = 0; m < 4; ++m) _Pragma("unroll") for (int n = 0; n < 2; ++n) _Pragma("unroll") for (int k = 0; k < 2; ++k) \
;         acc[ai][bj][m][n] = __builtin_amdgcn_mfma_f32_16x16x32_bf16(Bt[n][k], At[m][k], acc[ai][bj][m][n], 0, 0, 0); __builtin_amdgcn_s_setprio(0); } while (0)
; #define PG8_WAIT_V(n) asm volatile("s_waitcnt vmcnt(" #n ")" ::: "memory")
; #define PG8_WAIT_L(n) asm volatile("s_waitcnt lgkmcnt(" #n ")" ::: "memory")
; #define PG8_BAR __builtin_amdgcn_s_barrier()
; #define PG8_SCHED __builtin_amdgcn_sched_barrier(0)
; template <class Epi, class Sched, bool ALIGN_EPI = false, bool SP2 = false>
; __device__ __forceinline__ void gemm_phase(PG8_LAS unsigned char* lds, const Gemm g, const Sched& S, const Epi& E) {
;     ...
;             PG8_WAIT_V(8); PG8_WAIT_L(0); PG8_BAR; PG8_MMA(1, 0, At, B0); PG8_MMA(1, 1, At, B1); PG8_BAR; PG8_SCHED;
;             PG8_LDB(B0, 1, 0); PG8_LDB(B1, 1, 1); PG8_SCHED; PG8_LDA(At, 1, 0); PG8_STAGE(PG8_SA(0, 1), a2 + hstep, voffA);
;             PG8_WAIT_V(8); PG8_WAIT_L(0); PG8_BAR; PG8_MMA(0, 0, At, B0); PG8_MMA(0, 1, At, B1); PG8_BAR; PG8_SCHED;
	s_setprio 1
	s_waitcnt lgkmcnt(0)
	v_mfma_f32_16x16x32_bf16 v[60:63], v[128:131], v[160:163], v[60:63]
	v_mfma_f32_16x16x32_bf16 v[56:59], v[136:139], v[160:163], v[56:59]
	v_mfma_f32_16x16x32_bf16 v[44:47], v[128:131], v[178:181], v[44:47]
	v_mfma_f32_16x16x32_bf16 v[40:43], v[136:139], v[178:181], v[40:43]
	v_mfma_f32_16x16x32_bf16 v[28:31], v[128:131], v[186:189], v[28:31]
	v_mfma_f32_16x16x32_bf16 v[24:27], v[136:139], v[186:189], v[24:27]
	v_mfma_f32_16x16x32_bf16 v[12:15], v[128:131], v[194:197], v[12:15]
	v_mfma_f32_16x16x32_bf16 v[8:11], v[136:139], v[194:197], v[8:11]
	v_mfma_f32_16x16x32_bf16 v[60:63], v[132:135], v[164:167], v[60:63]
	v_mfma_f32_16x16x32_bf16 v[56:59], v[140:143], v[164:167], v[56:59]
	v_mfma_f32_16x16x32_bf16 v[44:47], v[132:135], v[182:185], v[44:47]
	v_mfma_f32_16x16x32_bf16 v[40:43], v[140:143], v[182:185], v[40:43]
	v_mfma_f32_16x16x32_bf16 v[28:31], v[132:135], v[190:193], v[28:31]
	v_mfma_f32_16x16x32_bf16 v[24:27], v[140:143], v[190:193], v[24:27]
	v_mfma_f32_16x16x32_bf16 v[12:15], v[132:135], v[214:217], v[12:15]
	v_mfma_f32_16x16x32_bf16 v[8:11], v[140:143], v[214:217], v[8:11]
	s_setprio 0
	s_setprio 1
	v_mfma_f32_16x16x32_bf16 v[52:55], v[144:147], v[160:163], v[52:55]
	v_mfma_f32_16x16x32_bf16 v[48:51], v[152:155], v[160:163], v[48:51]
	v_mfma_f32_16x16x32_bf16 v[36:39], v[144:147], v[178:181], v[36:39]
	v_mfma_f32_16x16x32_bf16 v[32:35], v[152:155], v[178:181], v[32:35]
	v_mfma_f32_16x16x32_bf16 v[20:23], v[144:147], v[186:189], v[20:23]
	v_mfma_f32_16x16x32_bf16 v[16:19], v[152:155], v[186:189], v[16:19]
	v_mfma_f32_16x16x32_bf16 v[4:7], v[144:147], v[194:197], v[4:7]
	v_mfma_f32_16x16x32_bf16 v[0:3], v[152:155], v[194:197], v[0:3]
	v_mfma_f32_16x16x32_bf16 v[52:55], v[148:151], v[164:167], v[52:55]
	v_mfma_f32_16x16x32_bf16 v[48:51], v[156:159], v[164:167], v[48:51]
	v_mfma_f32_16x16x32_bf16 v[36:39], v[148:151], v[182:185], v[36:39]
	v_mfma_f32_16x16x32_bf16 v[32:35], v[156:159], v[182:185], v[32:35]
	v_mfma_f32_16x16x32_bf16 v[20:23], v[148:151], v[190:193], v[20:23]
	v_mfma_f32_16x16x32_bf16 v[16:19], v[156:159], v[190:193], v[16:19]
	v_mfma_f32_16x16x32_bf16 v[4:7], v[148:151], v[214:217], v[4:7]
	v_mfma_f32_16x16x32_bf16 v[0:3], v[156:159], v[214:217], v[0:3]
	s_setprio 0
	s_barrier
	s_add_i32 s79, 0, 0x18000
	s_add_i32 s80, 0, 0x1c000
	v_add_u32_e32 v140, s79, v212
	v_add_u32_e32 v156, s80, v212
	ds_read_b128 v[128:131], v140
	ds_read_b128 v[132:135], v140 offset:1024
	ds_read_b128 v[136:139], v140 offset:2048
	ds_read_b128 v[140:143], v140 offset:3072
	ds_read_b128 v[144:147], v156
	ds_read_b128 v[148:151], v156 offset:1024
	ds_read_b128 v[152:155], v156 offset:2048
	ds_read_b128 v[156:159], v156 offset:3072
	s_add_u32 s40, s40, 0x80000
	s_addc_u32 s41, s41, 0
	s_mov_b32 m0, s61
	v_lshl_add_u64 v[224:225], s[40:41], 0, v[172:173]
	ds_read_b128 v[160:163], v213 offset:32768
	ds_read_b128 v[164:167], v213 offset:33792
	ds_read_b128 v[178:181], v213 offset:34816
	ds_read_b128 v[182:185], v213 offset:35840
	ds_read_b128 v[186:189], v213 offset:36864
	ds_read_b128 v[190:193], v213 offset:37888
	ds_read_b128 v[194:197], v213 offset:38912
	ds_read_b128 v[214:217], v213 offset:39936
	global_load_lds_dwordx4 v[224:225], off
	v_lshl_add_u64 v[224:225], s[40:41], 0, v[170:171]
	s_mov_b32 m0, s42
	s_nop 0
	global_load_lds_dwordx4 v[224:225], off
	s_waitcnt vmcnt(8)
	s_waitcnt lgkmcnt(0)
	s_barrier
	s_setprio 1
	s_waitcnt lgkmcnt(0)
	v_mfma_f32_16x16x32_bf16 v[124:127], v[128:131], v[160:163], v[124:127]
	v_mfma_f32_16x16x32_bf16 v[120:123], v[136:139], v[160:163], v[120:123]
	v_mfma_f32_16x16x32_bf16 v[108:111], v[128:131], v[178:181], v[108:111]
	v_mfma_f32_16x16x32_bf16 v[104:107], v[136:139], v[178:181], v[104:107]
	v_mfma_f32_16x16x32_bf16 v[92:95], v[128:131], v[186:189], v[92:95]
	v_mfma_f32_16x16x32_bf16 v[88:91], v[136:139], v[186:189], v[88:91]
	v_mfma_f32_16x16x32_bf16 v[76:79], v[128:131], v[194:197], v[76:79]
	v_mfma_f32_16x16x32_bf16 v[72:75], v[136:139], v[194:197], v[72:75]
	v_mfma_f32_16x16x32_bf16 v[124:127], v[132:135], v[164:167], v[124:127]
	v_mfma_f32_16x16x32_bf16 v[120:123], v[140:143], v[164:167], v[120:123]
	v_mfma_f32_16x16x32_bf16 v[108:111], v[132:135], v[182:185], v[108:111]
	v_mfma_f32_16x16x32_bf16 v[104:107], v[140:143], v[182:185], v[104:107]
	v_mfma_f32_16x16x32_bf16 v[92:95], v[132:135], v[190:193], v[92:95]
	v_mfma_f32_16x16x32_bf16 v[88:91], v[140:143], v[190:193], v[88:91]
	v_mfma_f32_16x16x32_bf16 v[76:79], v[132:135], v[214:217], v[76:79]
	v_mfma_f32_16x16x32_bf16 v[72:75], v[140:143], v[214:217], v[72:75]
	s_setprio 0
	s_setprio 1
	v_mfma_f32_16x16x32_bf16 v[116:119], v[144:147], v[160:163], v[116:119]
	v_mfma_f32_16x16x32_bf16 v[112:115], v[152:155], v[160:163], v[112:115]
	v_mfma_f32_16x16x32_bf16 v[100:103], v[144:147], v[178:181], v[100:103]
	v_mfma_f32_16x16x32_bf16 v[96:99], v[152:155], v[178:181], v[96:99]
	v_mfma_f32_16x16x32_bf16 v[84:87], v[144:147], v[186:189], v[84:87]
	v_mfma_f32_16x16x32_bf16 v[80:83], v[152:155], v[186:189], v[80:83]
	v_mfma_f32_16x16x32_bf16 v[68:71], v[144:147], v[194:197], v[68:71]
	v_mfma_f32_16x16x32_bf16 v[64:67], v[152:155], v[194:197], v[64:67]
	v_mfma_f32_16x16x32_bf16 v[116:119], v[148:151], v[164:167], v[116:119]
	v_mfma_f32_16x16x32_bf16 v[112:115], v[156:159], v[164:167], v[112:115]
	v_mfma_f32_16x16x32_bf16 v[100:103], v[148:151], v[182:185], v[100:103]
	v_mfma_f32_16x16x32_bf16 v[96:99], v[156:159], v[182:185], v[96:99]
	v_mfma_f32_16x16x32_bf16 v[84:87], v[148:151], v[190:193], v[84:87]
	v_mfma_f32_16x16x32_bf16 v[80:83], v[156:159], v[190:193], v[80:83]
	v_mfma_f32_16x16x32_bf16 v[68:71], v[148:151], v[214:217], v[68:71]
	v_mfma_f32_16x16x32_bf16 v[64:67], v[156:159], v[214:217], v[64:67]
	s_setprio 0
	s_barrier
; #define PG8_STAGE(bufoff, gbase, voff) do { _Pragma("unroll") for (int _i = 0; _i < 2; ++_i) \
;         __builtin_amdgcn_global_load_lds((const unsigned*)((const char*)(gbase) + (voff)[_i]), (PG8_LAS unsigned*)(lds + (bufoff) + ldsw + _i * 8192), 16, 0, 0); } while (0)
; #define PG8_LDA(dst, b, h) do { _Pragma("unroll") for (int m = 0; m < 4; ++m) _Pragma("unroll") for (int k = 0; k < 2; ++k) dst[m][k] = *(const PG8_LAS bf16x8*)(lds + PG8_SA(b, h) + aoff + m * 2048 + k * 1024); } while (0)
; #define PG8_MMA(ai, bj, At, Bt) do { __builtin_amdgcn_s_setprio(1); _Pragma("unroll") for (int m = 0; m < 4; ++m) _Pragma("unroll") for (int n = 0; n < 2; ++n) _Pragma("unroll") for (int k = 0; k < 2; ++k) \
;         acc[ai][bj][m][n] = __builtin_amdgcn_mfma_f32_16x16x32_bf16(Bt[n][k], At[m][k], acc[ai][bj][m][n], 0, 0, 0); __builtin_amdgcn_s_setprio(0); } while (0)
; #define PG8_WAIT_V(n) asm volatile("s_waitcnt vmcnt(" #n ")" ::: "memory")
; #define PG8_WAIT_L(n) asm volatile("s_waitcnt lgkmcnt(" #n ")" ::: "memory")
; #define PG8_BAR __builtin_amdgcn_s_barrier()
; #define PG8_SCHED __builtin_amdgcn_sched_barrier(0)
; template <class Epi, class Sched, bool ALIGN_EPI = false, bool SP2 = false>
; __device__ __forceinline__ void gemm_phase(PG8_LAS unsigned char* lds, const Gemm g, const Sched& S, const Epi& E) {
;     ...
;         for (int t = 0; t < nt; t += 2) {
;     ...
;             PG8_LDA(At, 1, 1); PG8_STAGE(PG8_SB(1, 0), b3, voffB); PG8_STAGE(PG8_SB(1, 1), b3 + hstep, voffB); PG8_STAGE(PG8_SA(1, 0), a3, voffA);
;             PG8_WAIT_V(8); PG8_WAIT_L(0); PG8_BAR; PG8_MMA(1, 0, At, B0); PG8_MMA(1, 1, At, B1); PG8_BAR; PG8_SCHED;
	s_add_i32 s40, s79, s44
	v_lshl_add_u64 v[198:199], v[198:199], 0, s[28:29]
	s_mov_b32 m0, s40
	ds_read_b128 v[160:163], v213 offset:49152
	ds_read_b128 v[164:167], v213 offset:50176
	ds_read_b128 v[178:181], v213 offset:51200
	ds_read_b128 v[182:185], v213 offset:52224
	ds_read_b128 v[186:189], v213 offset:53248
	ds_read_b128 v[190:193], v213 offset:54272
	ds_read_b128 v[194:197], v213 offset:55296
	ds_read_b128 v[214:217], v213 offset:56320
	global_load_lds_dwordx4 v[198:199], off
	s_add_i32 m0, s40, 0x2000
	s_add_u32 s8, s8, 0x80080
	v_lshl_add_u64 v[198:199], v[218:219], 0, s[28:29]
	s_addc_u32 s9, s9, 0
	s_add_i32 s40, s80, s44
	global_load_lds_dwordx4 v[198:199], off
	v_lshl_add_u64 v[198:199], s[8:9], 0, v[200:201]
	s_mov_b32 m0, s40
	s_nop 0
	global_load_lds_dwordx4 v[198:199], off
	v_lshl_add_u64 v[198:199], s[8:9], 0, v[168:169]
	s_add_i32 m0, s40, 0x2000
	s_nop 0
	global_load_lds_dwordx4 v[198:199], off
	v_lshl_add_u64 v[198:199], v[220:221], 0, s[28:29]
	s_mov_b32 m0, s5
	s_nop 0
	global_load_lds_dwordx4 v[198:199], off
	v_lshl_add_u64 v[198:199], v[222:223], 0, s[28:29]
	s_mov_b32 m0, s14
	s_nop 0
	global_load_lds_dwordx4 v[198:199], off
	s_waitcnt vmcnt(8)
	s_waitcnt lgkmcnt(0)
	s_barrier
	s_setprio 1
	s_waitcnt lgkmcnt(0)
	v_mfma_f32_16x16x32_bf16 v[60:63], v[128:131], v[160:163], v[60:63]
	v_mfma_f32_16x16x32_bf16 v[56:59], v[136:139], v[160:163], v[56:59]
	v_mfma_f32_16x16x32_bf16 v[44:47], v[128:131], v[178:181], v[44:47]
	v_mfma_f32_16x16x32_bf16 v[40:43], v[136:139], v[178:181], v[40:43]
	v_mfma_f32_16x16x32_bf16 v[28:31], v[128:131], v[186:189], v[28:31]
	v_mfma_f32_16x16x32_bf16 v[24:27], v[136:139], v[186:189], v[24:27]
	v_mfma_f32_16x16x32_bf16 v[12:15], v[128:131], v[194:197], v[12:15]
	v_mfma_f32_16x16x32_bf16 v[8:11], v[136:139], v[194:197], v[8:11]
	v_mfma_f32_16x16x32_bf16 v[60:63], v[132:135], v[164:167], v[60:63]
	v_mfma_f32_16x16x32_bf16 v[56:59], v[140:143], v[164:167], v[56:59]
	v_mfma_f32_16x16x32_bf16 v[44:47], v[132:135], v[182:185], v[44:47]
	v_mfma_f32_16x16x32_bf16 v[40:43], v[140:143], v[182:185], v[40:43]
	v_mfma_f32_16x16x32_bf16 v[28:31], v[132:135], v[190:193], v[28:31]
	v_mfma_f32_16x16x32_bf16 v[24:27], v[140:143], v[190:193], v[24:27]
	v_mfma_f32_16x16x32_bf16 v[12:15], v[132:135], v[214:217], v[12:15]
	v_mfma_f32_16x16x32_bf16 v[8:11], v[140:143], v[214:217], v[8:11]
	s_setprio 0
	s_setprio 1
	v_mfma_f32_16x16x32_bf16 v[52:55], v[144:147], v[160:163], v[52:55]
	v_mfma_f32_16x16x32_bf16 v[48:51], v[152:155], v[160:163], v[48:51]
	v_mfma_f32_16x16x32_bf16 v[36:39], v[144:147], v[178:181], v[36:39]
	v_mfma_f32_16x16x32_bf16 v[32:35], v[152:155], v[178:181], v[32:35]
	v_mfma_f32_16x16x32_bf16 v[20:23], v[144:147], v[186:189], v[20:23]
	v_mfma_f32_16x16x32_bf16 v[16:19], v[152:155], v[186:189], v[16:19]
	v_mfma_f32_16x16x32_bf16 v[4:7], v[144:147], v[194:197], v[4:7]
	v_mfma_f32_16x16x32_bf16 v[0:3], v[152:155], v[194:197], v[0:3]
	v_mfma_f32_16x16x32_bf16 v[52:55], v[148:151], v[164:167], v[52:55]
	v_mfma_f32_16x16x32_bf16 v[48:51], v[156:159], v[164:167], v[48:51]
	v_mfma_f32_16x16x32_bf16 v[36:39], v[148:151], v[182:185], v[36:39]
	v_mfma_f32_16x16x32_bf16 v[32:35], v[156:159], v[182:185], v[32:35]
	v_mfma_f32_16x16x32_bf16 v[20:23], v[148:151], v[190:193], v[20:23]
	v_mfma_f32_16x16x32_bf16 v[16:19], v[156:159], v[190:193], v[16:19]
	v_mfma_f32_16x16x32_bf16 v[4:7], v[148:151], v[214:217], v[4:7]
	v_mfma_f32_16x16x32_bf16 v[0:3], v[156:159], v[214:217], v[0:3]
	s_setprio 0
	s_barrier
	s_add_i32 s78, s78, 2
	s_add_u32 s6, s6, 0x100
	s_addc_u32 s7, s7, 0
	s_add_u32 s76, s76, 0x100
	s_addc_u32 s77, s77, 0
	s_cmp_gt_u32 s78, 29
	s_cbranch_scc0 .LBB0_65
	s_and_b64 vcc, exec, s[16:17]
	s_cbranch_vccz .LBB0_68
	s_barrier
